# SSD chunk loop: C.B^T and state-update LDS fragment reads prefetched ahead of their MFMAs
# speedup vs baseline: 1.0097x; 1.0027x over previous
; #define MFMA16(a, b, c) __builtin_amdgcn_mfma_f32_16x16x32_bf16((a), (b), (c), 0, 0, 0)
; __device__ __forceinline__ void ssd_prompt_item(const Params& p, int item, const int wv) {
;     ...
;     {
;       const float dl = __expf(alast);
;       bf16x8 btf[4];
; #pragma unroll
;       for (int ks = 0; ks < 4; ++ks) btf[ks] = *(const bf16x8*)(BT_l + (wid * 16 + fr) * 136 + ks * 32 + fq * 8);
; #pragma unroll
;       for (int pb = 0; pb < 4; ++pb) {
;         hacc[pb] = hacc[pb] * dl;
; #pragma unroll
;         for (int ks = 0; ks < 4; ++ks) {
;           bf16x8 xwf = *(const bf16x8*)(xw_l + (pb * 16 + fr) * 136 + ks * 32 + fq * 8);
;           hacc[pb] = MFMA16(btf[ks], xwf, hacc[pb]);
;         }
;       }
;     }
.LBB0_569:
	s_or_b64 exec, exec, s[84:85]
	v_mul_f32_e32 v96, 0x3fb8aa3b, v227
	s_waitcnt lgkmcnt(0)
	ds_read_b128 v[80:83], v221
	ds_read_b128 v[84:87], v221 offset:64
	ds_read_b128 v[88:91], v221 offset:128
	ds_read_b128 v[92:95], v221 offset:192
	v_exp_f32_e32 v100, v96
	ds_read_b128 v[32:35], v222
	ds_read_b128 v[36:39], v222 offset:64
	ds_read_b128 v[150:153], v222 offset:128
	ds_read_b128 v[154:157], v222 offset:192
	ds_read_b128 v[162:165], v222 offset:4352
	ds_read_b128 v[170:173], v222 offset:4416
	ds_read_b128 v[236:239], v222 offset:4480
	ds_read_b128 v[96:99], v222 offset:4544
	s_addk_i32 s40, 0x80
	s_mov_b64 s[84:85], 0x4000
	v_pk_mul_f32 v[66:67], v[66:67], v[100:101] op_sel_hi:[1,0]
	v_pk_mul_f32 v[64:65], v[64:65], v[100:101] op_sel_hi:[1,0]
	v_pk_mul_f32 v[78:79], v[78:79], v[100:101] op_sel_hi:[1,0]
	v_pk_mul_f32 v[76:77], v[76:77], v[100:101] op_sel_hi:[1,0]
	v_pk_mul_f32 v[74:75], v[74:75], v[100:101] op_sel_hi:[1,0]
	v_pk_mul_f32 v[72:73], v[72:73], v[100:101] op_sel_hi:[1,0]
	v_pk_mul_f32 v[70:71], v[70:71], v[100:101] op_sel_hi:[1,0]
	v_pk_mul_f32 v[68:69], v[68:69], v[100:101] op_sel_hi:[1,0]
	v_lshl_add_u64 v[176:177], v[176:177], 0, s[34:35]
	v_lshl_add_u64 v[178:179], v[178:179], 0, s[34:35]
	v_lshl_add_u64 v[180:181], v[180:181], 0, s[34:35]
	v_lshl_add_u64 v[182:183], v[182:183], 0, s[34:35]
	v_lshl_add_u64 v[184:185], v[184:185], 0, s[84:85]
	v_lshl_add_u64 v[186:187], v[186:187], 0, s[36:37]
	v_lshl_add_u64 v[188:189], v[188:189], 0, s[36:37]
	s_cmpk_lg_i32 s40, 0x800
	s_waitcnt lgkmcnt(8)
	s_waitcnt lgkmcnt(7)
	v_mfma_f32_16x16x32_bf16 v[64:67], v[80:83], v[32:35], v[64:67]
	ds_read_b128 v[32:35], v222 offset:8704
	s_waitcnt lgkmcnt(7)
	v_mfma_f32_16x16x32_bf16 v[64:67], v[84:87], v[36:39], v[64:67]
	ds_read_b128 v[36:39], v222 offset:8768
	s_waitcnt lgkmcnt(7)
	v_mfma_f32_16x16x32_bf16 v[64:67], v[88:91], v[150:153], v[64:67]
	ds_read_b128 v[150:153], v222 offset:8832
	s_waitcnt lgkmcnt(7)
	v_mfma_f32_16x16x32_bf16 v[64:67], v[92:95], v[154:157], v[64:67]
	ds_read_b128 v[154:157], v222 offset:8896
	s_waitcnt lgkmcnt(7)
	v_mfma_f32_16x16x32_bf16 v[76:79], v[80:83], v[162:165], v[76:79]
	ds_read_b128 v[162:165], v222 offset:13056
	s_waitcnt lgkmcnt(7)
	v_mfma_f32_16x16x32_bf16 v[76:79], v[84:87], v[170:173], v[76:79]
	ds_read_b128 v[170:173], v222 offset:13120
	s_waitcnt lgkmcnt(7)
	v_mfma_f32_16x16x32_bf16 v[76:79], v[88:91], v[236:239], v[76:79]
	ds_read_b128 v[236:239], v222 offset:13184
	s_waitcnt lgkmcnt(7)
	v_mfma_f32_16x16x32_bf16 v[76:79], v[92:95], v[96:99], v[76:79]
	ds_read_b128 v[96:99], v222 offset:13248
	s_waitcnt lgkmcnt(7)
	v_mfma_f32_16x16x32_bf16 v[72:75], v[80:83], v[32:35], v[72:75]
	s_waitcnt lgkmcnt(6)
	v_mfma_f32_16x16x32_bf16 v[72:75], v[84:87], v[36:39], v[72:75]
	s_waitcnt lgkmcnt(5)
	v_mfma_f32_16x16x32_bf16 v[72:75], v[88:91], v[150:153], v[72:75]
	s_waitcnt lgkmcnt(4)
	v_mfma_f32_16x16x32_bf16 v[72:75], v[92:95], v[154:157], v[72:75]
	s_waitcnt lgkmcnt(3)
	v_mfma_f32_16x16x32_bf16 v[68:71], v[80:83], v[162:165], v[68:71]
	s_waitcnt lgkmcnt(2)
	v_mfma_f32_16x16x32_bf16 v[68:71], v[84:87], v[170:173], v[68:71]
	s_waitcnt lgkmcnt(1)
	v_mfma_f32_16x16x32_bf16 v[68:71], v[88:91], v[236:239], v[68:71]
	s_waitcnt lgkmcnt(0)
	v_mfma_f32_16x16x32_bf16 v[68:71], v[92:95], v[96:99], v[68:71]
	s_cbranch_scc0 .LBB0_565

; #define MFMA16(a, b, c) __builtin_amdgcn_mfma_f32_16x16x32_bf16((a), (b), (c), 0, 0, 0)
; __device__ __forceinline__ void ssd_prompt_item(const Params& p, int item, const int wv) {
;     ...
;     u32x2 zsr[4];
; #pragma unroll
;     for (int pb = 0; pb < 4; ++pb) zsr[pb] = *(const u32x2*)(ZS + (size_t)(t0 + wid * 16 + fr) * 1024 + h * 64 + pb * 16 + fq * 4);
;     bf16x8 cf[4];
; #pragma unroll
;     for (int ks = 0; ks < 4; ++ks) cf[ks] = *(const bf16x8*)(C_l + (wid * 16 + fr) * 136 + ks * 32 + fq * 8);
;     f32x4 cb[8];
; #pragma unroll
;     for (int jb = 0; jb < 8; ++jb) {
;       cb[jb] = (f32x4){0.f, 0.f, 0.f, 0.f};
;       if (jb <= wid) {
; #pragma unroll
;         for (int ks = 0; ks < 4; ++ks) { bf16x8 bf = *(const bf16x8*)(B_l + (jb * 16 + fr) * 136 + ks * 32 + fq * 8); cb[jb] = MFMA16(bf, cf[ks], cb[jb]); }
;       }
;     }
.LBB0_579:
	v_add_u32_e32 v142, v195, v196
	ds_read_b128 v[88:91], v142
	ds_read_b128 v[84:87], v142 offset:64
	ds_read_b128 v[80:83], v142 offset:128
	ds_read_b128 v[92:95], v142 offset:192
	ds_read_b128 v[32:35], v223 offset:34816
	ds_read_b128 v[36:39], v223 offset:34880
	ds_read_b128 v[150:153], v223 offset:34944
	ds_read_b128 v[154:157], v223 offset:35008
	ds_read_b128 v[162:165], v223 offset:39168
	ds_read_b128 v[170:173], v223 offset:39232
	ds_read_b128 v[236:239], v223 offset:39296
	v_lshl_add_u64 v[108:109], s[50:51], 0, v[186:187]
	v_readlane_b32 s84, v251, 4
	v_readlane_b32 s85, v251, 5
	s_andn2_b64 vcc, exec, s[84:85]
	v_mov_b32_e32 v120, 0
	v_mov_b32_e32 v121, 0
	v_mov_b32_e32 v122, 0
	v_mov_b32_e32 v123, 0
	global_load_dwordx2 v[138:139], v[108:109], off offset:-64
	global_load_dwordx2 v[136:137], v[108:109], off offset:-32
	global_load_dwordx2 v[134:135], v[108:109], off
	global_load_dwordx2 v[132:133], v[108:109], off offset:32
	s_waitcnt lgkmcnt(6)
	v_mfma_f32_16x16x32_bf16 v[124:127], v[32:35], v[88:91], 0
	ds_read_b128 v[32:35], v223 offset:39360
	s_waitcnt lgkmcnt(6)
	v_mfma_f32_16x16x32_bf16 v[124:127], v[36:39], v[84:87], v[124:127]
	s_waitcnt lgkmcnt(5)
	v_mfma_f32_16x16x32_bf16 v[124:127], v[150:153], v[80:83], v[124:127]
	s_waitcnt lgkmcnt(4)
	v_mfma_f32_16x16x32_bf16 v[124:127], v[154:157], v[92:95], v[124:127]
	s_nop 5
	v_cndmask_b32_e64 v97, 0, 1, s[84:85]
	v_mov_b32_e32 v96, 0
	v_cmp_ne_u32_e64 s[96:97], 1, v97
	s_cbranch_vccnz .LBB0_581
	ds_read_b128 v[36:39], v223 offset:43520
	ds_read_b128 v[150:153], v223 offset:43584
	ds_read_b128 v[154:157], v223 offset:43648
	s_waitcnt lgkmcnt(6)
	v_mfma_f32_16x16x32_bf16 v[120:123], v[162:165], v[88:91], 0
	ds_read_b128 v[162:165], v223 offset:43712
	s_waitcnt lgkmcnt(6)
	v_mfma_f32_16x16x32_bf16 v[120:123], v[170:173], v[84:87], v[120:123]
	s_waitcnt lgkmcnt(5)
	v_mfma_f32_16x16x32_bf16 v[120:123], v[236:239], v[80:83], v[120:123]
	s_waitcnt lgkmcnt(4)
	v_mfma_f32_16x16x32_bf16 v[120:123], v[32:35], v[92:95], v[120:123]
.LBB0_581:
	v_cndmask_b32_e64 v97, 0, 1, s[2:3]
	v_cmp_ne_u32_e64 s[84:85], 1, v97
	s_andn2_b64 vcc, exec, s[2:3]
	v_mov_b32_e32 v116, 0
	v_mov_b32_e32 v117, 0
	v_mov_b32_e32 v118, 0
	v_mov_b32_e32 v119, 0
	s_cbranch_vccnz .LBB0_583
	ds_read_b128 v[170:173], v223 offset:47872
	ds_read_b128 v[236:239], v223 offset:47936
	ds_read_b128 v[32:35], v223 offset:48000
	s_waitcnt lgkmcnt(6)
	v_mfma_f32_16x16x32_bf16 v[116:119], v[36:39], v[88:91], 0
	ds_read_b128 v[36:39], v223 offset:48064
	s_waitcnt lgkmcnt(6)
	v_mfma_f32_16x16x32_bf16 v[116:119], v[150:153], v[84:87], v[116:119]
	s_waitcnt lgkmcnt(5)
	v_mfma_f32_16x16x32_bf16 v[116:119], v[154:157], v[80:83], v[116:119]
	s_waitcnt lgkmcnt(4)
	v_mfma_f32_16x16x32_bf16 v[116:119], v[162:165], v[92:95], v[116:119]
.LBB0_583:
	v_cndmask_b32_e64 v97, 0, 1, s[14:15]
	v_cmp_ne_u32_e64 s[94:95], 1, v97
	s_andn2_b64 vcc, exec, s[14:15]
	v_mov_b32_e32 v97, 0
	s_nop 0
	v_mov_b32_e32 v98, 0
	v_mov_b32_e32 v99, 0
	s_cbranch_vccnz .LBB0_585
	ds_read_b128 v[150:153], v223 offset:52224
	ds_read_b128 v[154:157], v223 offset:52288
	ds_read_b128 v[162:165], v223 offset:52352
	s_waitcnt lgkmcnt(6)
	v_mfma_f32_16x16x32_bf16 v[96:99], v[170:173], v[88:91], 0
	ds_read_b128 v[170:173], v223 offset:52416
	s_waitcnt lgkmcnt(6)
	v_mfma_f32_16x16x32_bf16 v[96:99], v[236:239], v[84:87], v[96:99]
	s_waitcnt lgkmcnt(5)
	v_mfma_f32_16x16x32_bf16 v[96:99], v[32:35], v[80:83], v[96:99]
	s_waitcnt lgkmcnt(4)
	v_mfma_f32_16x16x32_bf16 v[96:99], v[36:39], v[92:95], v[96:99]
.LBB0_585:
	v_cndmask_b32_e64 v100, 0, 1, s[16:17]
	v_mov_b32_e32 v104, 0
	v_cmp_ne_u32_e64 s[86:87], 1, v100
	s_andn2_b64 vcc, exec, s[16:17]
	v_mov_b32_e32 v112, 0
	v_mov_b32_e32 v113, 0
	v_mov_b32_e32 v114, 0
	v_mov_b32_e32 v115, 0
	s_cbranch_vccnz .LBB0_587
	ds_read_b128 v[236:239], v223 offset:56576
	ds_read_b128 v[32:35], v223 offset:56640
	ds_read_b128 v[36:39], v223 offset:56704
	s_waitcnt lgkmcnt(6)
	v_mfma_f32_16x16x32_bf16 v[112:115], v[150:153], v[88:91], 0
	ds_read_b128 v[150:153], v223 offset:56768
	s_waitcnt lgkmcnt(6)
	v_mfma_f32_16x16x32_bf16 v[112:115], v[154:157], v[84:87], v[112:115]
	s_waitcnt lgkmcnt(5)
	v_mfma_f32_16x16x32_bf16 v[112:115], v[162:165], v[80:83], v[112:115]
	s_waitcnt lgkmcnt(4)
	v_mfma_f32_16x16x32_bf16 v[112:115], v[170:173], v[92:95], v[112:115]
.LBB0_587:
	s_nop 4
	v_cndmask_b32_e64 v100, 0, 1, s[26:27]
	v_cmp_ne_u32_e64 s[92:93], 1, v100
	s_andn2_b64 vcc, exec, s[26:27]
	v_mov_b32_e32 v105, 0
	v_mov_b32_e32 v106, 0
	v_mov_b32_e32 v107, 0
	s_cbranch_vccnz .LBB0_589
	ds_read_b128 v[154:157], v223 offset:60928
	ds_read_b128 v[162:165], v223 offset:60992
	ds_read_b128 v[170:173], v223 offset:61056
	s_waitcnt lgkmcnt(6)
	v_mfma_f32_16x16x32_bf16 v[104:107], v[236:239], v[88:91], 0
	ds_read_b128 v[236:239], v223 offset:61120
	s_waitcnt lgkmcnt(6)
	v_mfma_f32_16x16x32_bf16 v[104:107], v[32:35], v[84:87], v[104:107]
	s_waitcnt lgkmcnt(5)
	v_mfma_f32_16x16x32_bf16 v[104:107], v[36:39], v[80:83], v[104:107]
	s_waitcnt lgkmcnt(4)
	v_mfma_f32_16x16x32_bf16 v[104:107], v[150:153], v[92:95], v[104:107]
.LBB0_589:
	s_nop 4
	v_cndmask_b32_e64 v101, 0, 1, s[28:29]
	v_mov_b32_e32 v100, 0
	v_cmp_ne_u32_e64 s[88:89], 1, v101
	s_andn2_b64 vcc, exec, s[28:29]
	v_mov_b32_e32 v108, 0
	v_mov_b32_e32 v109, 0
	v_mov_b32_e32 v110, 0
	v_mov_b32_e32 v111, 0
	s_cbranch_vccnz .LBB0_591
	ds_read_b128 v[32:35], v223 offset:65280
	ds_read_b128 v[36:39], v223 offset:65344
	ds_read_b128 v[150:153], v223 offset:65408
	s_waitcnt lgkmcnt(6)
	v_mfma_f32_16x16x32_bf16 v[108:111], v[154:157], v[88:91], 0
	ds_read_b128 v[154:157], v223 offset:65472
	s_waitcnt lgkmcnt(6)
	v_mfma_f32_16x16x32_bf16 v[108:111], v[162:165], v[84:87], v[108:111]
	s_waitcnt lgkmcnt(5)
	v_mfma_f32_16x16x32_bf16 v[108:111], v[170:173], v[80:83], v[108:111]
	s_waitcnt lgkmcnt(4)
	v_mfma_f32_16x16x32_bf16 v[108:111], v[236:239], v[92:95], v[108:111]
.LBB0_591:
	v_cndmask_b32_e64 v101, 0, 1, s[30:31]
	v_cmp_ne_u32_e64 s[90:91], 1, v101
	s_andn2_b64 vcc, exec, s[30:31]
	v_mov_b32_e32 v101, 0
	v_mov_b32_e32 v102, 0
	v_mov_b32_e32 v103, 0
	s_cbranch_vccnz .LBB0_593
	s_waitcnt lgkmcnt(3)
	v_mfma_f32_16x16x32_bf16 v[100:103], v[32:35], v[88:91], 0
	s_waitcnt lgkmcnt(2)
	v_mfma_f32_16x16x32_bf16 v[100:103], v[36:39], v[84:87], v[100:103]
	s_waitcnt lgkmcnt(1)
	v_mfma_f32_16x16x32_bf16 v[100:103], v[150:153], v[80:83], v[100:103]
	s_waitcnt lgkmcnt(0)
	v_mfma_f32_16x16x32_bf16 v[100:103], v[154:157], v[92:95], v[100:103]
